# retention: Qs/Ks/St LDS rows chunk-permuted for conflict-free ds_read_b128 operand reads + one-ahead LDS read pipelining in steps 1, 2 and 4
# speedup vs baseline: 1.0150x; 1.0150x over previous
.LBB0_431:
	s_andn2_b64 vcc, exec, s[16:17]
	s_cbranch_vccnz .LBB0_490
	v_readlane_b32 s4, v253, 46
	v_mov_b32_e32 v2, v238
	v_readlane_b32 s5, v253, 47
	s_andn2_b64 vcc, exec, s[4:5]
	v_readfirstlane_b32 s11, v2
	s_cbranch_vccnz .LBB0_440
	s_add_u32 s16, s78, 0x41a00000
	s_addc_u32 s17, s79, 0
	s_add_u32 s18, s78, 0x45a00000
	s_addc_u32 s19, s79, 0
	s_add_u32 s20, s78, 0x49a00000
	s_addc_u32 s21, s79, 0
	s_add_u32 s7, s78, 0x59a00000
	s_addc_u32 s10, s79, 0
	s_movk_i32 s12, 0x840
	v_ashrrev_i32_e32 v78, 3, v2
	s_waitcnt lgkmcnt(0)
	v_and_b32_e32 v6, 7, v2
	s_ashr_i32 s13, s11, 3
	v_cmp_gt_i32_e32 vcc, s12, v2
	v_lshlrev_b32_e32 v4, 3, v6
	v_lshlrev_b32_e32 v12, 4, v6
	v_sub_u32_e32 v6, 63, v78
	s_lshr_b32 s12, s11, 5
	v_bfi_b32 v13, -16, s13, v2
	s_movk_i32 s8, 0x210
	v_bfe_u32 v3, v2, 4, 2
	v_cvt_f32_i32_e32 v91, v6
	s_and_b32 s12, s12, 2
	v_mul_lo_u32 v6, v13, s8
	v_and_b32_e32 v1, 15, v2
	s_and_b32 s14, s13, -16
	v_add_u32_e32 v14, 0, v6
	s_lshl_b32 s15, s12, 4
	v_lshlrev_b32_e32 v6, 2, v3
	v_or_b32_e32 v16, s15, v1
	v_or_b32_e32 v18, s14, v6
	v_sub_u32_e32 v27, v18, v16
	v_sub_u32_e32 v28, 0, v27
	v_or_b32_e32 v19, 16, v16
	v_max_i32_e32 v27, v27, v28
	v_cvt_f32_u32_e32 v129, v27
	v_sub_u32_e32 v27, v18, v19
	v_sub_u32_e32 v28, 0, v27
	s_movk_i32 s4, 0x90
	v_max_i32_e32 v27, v27, v28
	v_readlane_b32 s36, v254, 19
	v_cvt_f32_u32_e32 v130, v27
	v_mul_lo_u32 v27, v18, s4
	v_add_u32_e32 v131, s36, v27
	v_or_b32_e32 v27, 1, v18
	v_sub_u32_e32 v28, v27, v16
	v_sub_u32_e32 v29, 0, v28
	v_max_i32_e32 v28, v28, v29
	v_sub_u32_e32 v27, v27, v19
	v_cvt_f32_u32_e32 v132, v28
	v_sub_u32_e32 v28, 0, v27
	v_max_i32_e32 v27, v27, v28
	v_cvt_f32_u32_e32 v133, v27
	v_or_b32_e32 v27, 2, v18
	v_sub_u32_e32 v28, v27, v16
	v_sub_u32_e32 v29, 0, v28
	v_readlane_b32 s9, v254, 18
	v_max_i32_e32 v28, v28, v29
	v_sub_u32_e32 v27, v27, v19
	v_mov_b32_e32 v20, s9
	v_cvt_f32_u32_e32 v135, v28
	v_sub_u32_e32 v28, 0, v27
	v_or_b32_e32 v18, 3, v18
	v_mad_u32_u24 v17, v16, s8, 0
	v_lshlrev_b32_e32 v126, 1, v16
	v_mad_u32_u24 v20, v16, s8, v20
	v_max_i32_e32 v27, v27, v28
	v_sub_u32_e32 v16, v18, v16
	v_cvt_f32_u32_e32 v136, v27
	v_sub_u32_e32 v27, 0, v16
	v_max_i32_e32 v16, v16, v27
	v_cvt_f32_u32_e32 v138, v16
	v_sub_u32_e32 v16, v18, v19
	v_add_u32_e32 v21, 1, v13
	v_sub_u32_e32 v18, 0, v16
	v_lshlrev_b32_e32 v5, 3, v2
	v_lshlrev_b32_e32 v15, 4, v3
	v_cvt_f32_i32_e32 v128, v21
	v_bfe_u32 v21, v2, 2, 2
	v_lshlrev_b32_e32 v3, 3, v3
	v_max_i32_e32 v16, v16, v18
	v_and_b32_e32 v7, 0xf8, v5
	v_and_b32_e32 v5, 24, v5
	s_ashr_i32 s22, s14, 31
	v_or_b32_e32 v80, s14, v1
	s_and_b32 s14, s11, 0xffffffc0
	v_cvt_f32_u32_e32 v139, v16
	v_or_b32_e32 v16, v3, v21
	v_mul_lo_u32 v10, v78, s4
	v_mul_lo_u32 v13, v13, s4
	s_lshl_b32 s12, s12, 5
	v_or_b32_e32 v22, s14, v5
	v_mad_u32_u24 v5, v16, s4, v5
	v_readlane_b32 s4, v254, 20
	v_readlane_b32 s5, v254, 16
	v_lshlrev_b32_e32 v127, 1, v19
	s_or_b32 s13, s12, 32
	v_add_u32_e32 v19, s4, v5
	v_add_u32_e32 v18, s5, v5
	v_add_u32_e32 v142, s12, v19
	v_add_u32_e32 v144, s13, v19
	v_add_u32_e32 v19, 0x1200, v5
	v_readlane_b32 s6, v254, 17
	v_add_u32_e32 v13, s36, v13
	v_mov_b32_e32 v81, s22
	v_add_u32_e32 v141, s12, v18
	v_add_u32_e32 v143, s13, v18
	v_or_b32_e32 v18, 32, v16
	v_add_u32_e32 v21, s5, v19
	v_add_u32_e32 v27, s4, v19
	v_readlane_b32 s22, v254, 25
	v_readlane_b32 s36, v254, 26
	v_readlane_b32 s37, v254, 27
	v_readlane_b32 s38, v254, 28
	v_readlane_b32 s39, v254, 29
	v_readlane_b32 s40, v254, 30
	v_readlane_b32 s41, v254, 31
	v_add_u32_e32 v145, s12, v21
	v_add_u32_e32 v146, s12, v27
	v_mad_u32_u24 v16, v16, s8, v22
	v_add_u32_e32 v150, s6, v5
	v_readlane_b32 s12, v254, 23
	v_add_u32_e32 v154, s22, v5
	v_add_u32_e32 v155, s36, v5
	v_add_u32_e32 v156, s37, v5
	v_add_u32_e32 v157, s38, v5
	v_add_u32_e32 v158, s39, v5
	v_add_u32_e32 v159, s40, v5
	v_add_u32_e32 v160, s41, v5
	v_mad_u32_u24 v5, v18, s8, v22
	v_add_u32_e32 v11, s5, v10
	v_add_u32_e32 v23, 0x200, v2
	v_add_u32_e32 v147, s13, v21
	v_add_u32_e32 v148, s13, v27
	v_readlane_b32 s4, v254, 21
	v_readlane_b32 s5, v254, 22
	v_add_u32_e32 v152, s12, v16
	v_readlane_b32 s13, v254, 24
	v_add_u32_e32 v164, s12, v5
	s_add_i32 s12, s9, s14
	v_ashrrev_i32_e32 v84, 5, v23
	v_add_u32_e32 v23, 0x400, v2
	v_add_u32_e32 v161, s4, v5
	v_add_u32_e32 v163, s5, v5
	v_add_u32_e32 v165, s13, v5
	v_add_u32_e32 v5, s12, v3
	s_add_i32 s12, s14, 0
	v_ashrrev_i32_e32 v79, 31, v78
	v_lshlrev_b32_e32 v8, 4, v2
	v_ashrrev_i32_e32 v86, 5, v23
	v_add_u32_e32 v23, 0x600, v2
	s_add_i32 s12, s12, 0x10820
	v_and_b32_e32 v9, 0x1f0, v8
	v_ashrrev_i32_e32 v82, 5, v2
	v_ashrrev_i32_e32 v88, 5, v23
	v_add_u32_e32 v149, s4, v16
	v_add_u32_e32 v151, s5, v16
	v_add_u32_e32 v153, s13, v16
	v_add_u32_e32 v16, s12, v3
	v_add_u32_e32 v173, 0xfffffe00, v2
	v_and_or_b32 v90, s11, 64, v3
	v_lshlrev_b64 v[2:3], 13, v[78:79]
	v_add_u32_e32 v9, 0, v9
	v_add_u32_e32 v10, s6, v10
	v_ashrrev_i32_e32 v83, 31, v82
	v_ashrrev_i32_e32 v85, 31, v84
	v_ashrrev_i32_e32 v87, 31, v86
	v_ashrrev_i32_e32 v89, 31, v88
	v_mul_lo_u32 v23, v82, s8
	v_mul_lo_u32 v24, v84, s8
	v_mul_lo_u32 v25, v86, s8
	v_mul_lo_u32 v26, v88, s8
	v_mul_u32_u24_e32 v1, 0x210, v1
	v_or_b32_e32 v2, v2, v12
	s_mov_b64 s[12:13], 0x49a80000
	v_add_u32_e32 v134, 0x90, v131
	v_add_u32_e32 v137, 0x120, v131
	v_add_u32_e32 v140, 0x1b0, v131
	v_add_u32_e32 v162, s6, v19
	v_add_u32_e32 v166, s22, v19
	v_add_u32_e32 v167, s36, v19
	v_add_u32_e32 v168, s37, v19
	v_add_u32_e32 v169, s38, v19
	v_add_u32_e32 v170, s39, v19
	v_add_u32_e32 v171, s40, v19
	v_add_u32_e32 v172, s41, v19
	v_add_u32_e32 v174, s9, v8
	v_lshl_add_u64 v[92:93], v[2:3], 0, s[12:13]
	v_lshlrev_b64 v[94:95], 9, v[88:89]
	v_lshlrev_b64 v[96:97], 9, v[86:87]
	v_lshlrev_b64 v[98:99], 9, v[84:85]
	v_lshlrev_b64 v[100:101], 9, v[82:83]
	v_and_b32_e32 v239, 7, v238
	v_lshlrev_b32_e32 v175, 6, v239
	v_bfe_u32 v239, v238, 3, 1
	v_lshl_or_b32 v175, v239, 5, v175
	v_bfe_u32 v239, v238, 4, 1
	v_lshl_or_b32 v175, v239, 4, v175
	v_lshlrev_b32_e32 v102, 1, v4
	v_lshlrev_b32_e32 v186, 1, v6
	s_lshl_b32 s56, s15, 1
	v_add_u32_e32 v176, v9, v23
	v_add_u32_e32 v177, v9, v24
	v_add_u32_e32 v178, v9, v25
	v_add_u32_e32 v179, v9, v26
	v_add_u32_e32 v180, v11, v12
	v_add_u32_e32 v181, v10, v12
	v_add_u32_e32 v182, v14, v15
	v_add_u32_e32 v183, v17, v15
	v_add_u32_e32 v184, v20, v15
	v_add_u32_e32 v185, v13, v15
	v_add_u32_e32 v196, v5, v1
	v_add_u32_e32 v197, v16, v1
	v_readlane_b32 s11, v254, 13
	s_mov_b32 s12, s2
	v_readlane_b32 s13, v254, 12
	s_mov_b32 s14, s2
	v_bfe_u32 v244, v238, 4, 2
	v_lshlrev_b32_e32 v245, 4, v244
	v_and_b32_e32 v246, 1, v244
	v_lshrrev_b32_e32 v244, 1, v244
	v_lshlrev_b32_e32 v246, 8, v246
	v_lshl_add_u32 v246, v244, 7, v246
	v_sub_u32_e32 v246, v246, v245
	v_add_u32_e32 v182, v182, v246
	v_add_u32_e32 v183, v183, v246
	v_add_u32_e32 v184, v184, v246
	v_lshrrev_b32_e32 v245, 6, v238
	v_mul_u32_u24_e32 v245, 48, v245
	v_mul_u32_u24_e32 v246, 0xf0, v244
	v_sub_u32_e32 v246, v246, v245
	v_add_u32_e32 v196, v196, v246
	v_add_u32_e32 v197, v197, v246
	v_add_u32_e32 v197, 0x60, v197
	v_bfe_u32 v244, v238, 1, 1
	v_mul_u32_u24_e32 v246, 0xf0, v244
	v_sub_u32_e32 v246, v246, v245
	v_add_u32_e32 v149, v149, v246
	v_add_u32_e32 v151, v151, v246
	v_add_u32_e32 v161, v161, v246
	v_add_u32_e32 v163, v163, v246
	v_add_u32_e32 v246, 0x60, v246
	v_add_u32_e32 v152, v152, v246
	v_add_u32_e32 v153, v153, v246
	v_add_u32_e32 v164, v164, v246
	v_add_u32_e32 v165, v165, v246

.LBB0_438:
	s_waitcnt vmcnt(2)
	ds_write_b128 v176, v[2:5]
	ds_write_b128 v176, v[6:9] offset:33792
	ds_write_b128 v177, v[10:13]
	ds_write_b128 v177, v[14:17] offset:33792
	ds_write_b128 v178, v[18:21]
	ds_write_b128 v178, v[22:25] offset:33792
	ds_write_b128 v179, v[30:33]
	ds_write_b128 v179, v[34:37] offset:33792
	ds_write_b128 v180, v[26:29]
	v_lshlrev_b32_e32 v2, 16, v26
	v_and_b32_e32 v3, 0xffff0000, v26
	v_lshlrev_b32_e32 v4, 16, v27
	v_and_b32_e32 v5, 0xffff0000, v27
	v_pk_mul_f32 v[2:3], v[124:125], v[2:3]
	v_pk_mul_f32 v[4:5], v[124:125], v[4:5]
	v_cvt_pk_bf16_f32 v2, v2, v3
	v_cvt_pk_bf16_f32 v3, v4, v5
	v_lshlrev_b32_e32 v4, 16, v28
	v_and_b32_e32 v5, 0xffff0000, v28
	v_lshlrev_b32_e32 v6, 16, v29
	v_and_b32_e32 v7, 0xffff0000, v29
	v_pk_mul_f32 v[4:5], v[124:125], v[4:5]
	v_pk_mul_f32 v[6:7], v[124:125], v[6:7]
	v_cvt_pk_bf16_f32 v4, v4, v5
	v_cvt_pk_bf16_f32 v5, v6, v7
	v_lshl_add_u64 v[6:7], s[78:79], 0, v[122:123]
	ds_write_b128 v181, v[2:5]
	v_add_co_u32_e64 v2, s[36:37], s27, v6
	v_lshl_add_u64 v[14:15], s[78:79], 0, v[120:121]
	s_nop 0
	v_addc_co_u32_e64 v3, s[36:37], 0, v7, s[36:37]
	v_add_co_u32_e64 v6, s[36:37], s28, v6
	v_lshl_add_u64 v[22:23], s[78:79], 0, v[118:119]
	s_nop 0
	v_addc_co_u32_e64 v7, s[36:37], 0, v7, s[36:37]
	v_add_co_u32_e64 v10, s[36:37], s27, v14
	v_lshl_add_u64 v[26:27], s[78:79], 0, v[116:117]
	s_nop 0
	v_addc_co_u32_e64 v11, s[36:37], 0, v15, s[36:37]
	v_add_co_u32_e64 v14, s[36:37], s28, v14
	s_waitcnt lgkmcnt(0)
	s_nop 0
	v_addc_co_u32_e64 v15, s[36:37], 0, v15, s[36:37]
	v_add_co_u32_e64 v18, s[36:37], s27, v22
	s_barrier
	s_nop 0
	v_addc_co_u32_e64 v19, s[36:37], 0, v23, s[36:37]
	v_add_co_u32_e64 v22, s[36:37], s28, v22
	s_nop 1
	v_addc_co_u32_e64 v23, s[36:37], 0, v23, s[36:37]
	v_add_co_u32_e64 v28, s[36:37], s27, v26
	global_load_dwordx4 v[2:5], v[2:3], off
	s_nop 0
	v_addc_co_u32_e64 v29, s[36:37], 0, v27, s[36:37]
	v_add_co_u32_e64 v26, s[36:37], s28, v26
	global_load_dwordx4 v[30:33], v[28:29], off
	s_nop 0
	v_addc_co_u32_e64 v27, s[36:37], 0, v27, s[36:37]
	global_load_dwordx4 v[34:37], v[26:27], off
	v_lshl_add_u64 v[26:27], s[78:79], 0, v[114:115]
	global_load_dwordx4 v[6:9], v[6:7], off
	v_add_u32_e32 v205, v131, v127
	global_load_dwordx4 v[10:13], v[10:11], off
	s_mov_b32 s36, 0x59a00000
	global_load_dwordx4 v[14:17], v[14:15], off
	v_mov_b32_e32 v105, v104
	global_load_dwordx4 v[18:21], v[18:19], off
	v_pk_mul_f32 v[68:69], v[104:105], v[68:69]
	global_load_dwordx4 v[22:25], v[22:23], off
	v_pk_mul_f32 v[66:67], v[106:107], v[66:67]
	global_load_dwordx4 v[26:29], v[26:27], off
	ds_read_b128 v[70:73], v182
	ds_read_b128 v[74:77], v183 offset:33792
	ds_read_b128 v[188:191], v183 offset:42240
	ds_read_b128 v[210:213], v182 offset:16
	ds_read_b128 v[214:217], v183 offset:33808
	ds_read_b128 v[218:221], v183 offset:42256
	s_waitcnt lgkmcnt(4)
	v_mfma_f32_16x16x32_bf16 v[74:77], v[70:73], v[74:77], 0
	v_mul_f32_e64 v64, v104, v64
	v_mul_f32_e64 v65, v105, v65
	v_pk_mul_f32 v[62:63], v[106:107], v[62:63]
	v_pk_mul_f32 v[60:61], v[104:105], v[60:61]
	s_waitcnt lgkmcnt(3)
	v_mfma_f32_16x16x32_bf16 v[70:73], v[70:73], v[188:191], 0
	ds_read_b128 v[188:191], v182 offset:32
	ds_read_b128 v[192:195], v183 offset:33824
	ds_read_b128 v[206:209], v183 offset:42272
	v_pk_mul_f32 v[58:59], v[106:107], v[58:59]
	v_pk_mul_f32 v[48:49], v[104:105], v[48:49]
	s_waitcnt lgkmcnt(4)
	v_mfma_f32_16x16x32_bf16 v[74:77], v[210:213], v[214:217], v[74:77]
	v_mul_f32_e64 v46, v106, v46
	v_mul_f32_e64 v47, v107, v47
	v_pk_mul_f32 v[44:45], v[104:105], v[44:45]
	v_pk_mul_f32 v[42:43], v[106:107], v[42:43]
	s_waitcnt lgkmcnt(3)
	v_mfma_f32_16x16x32_bf16 v[70:73], v[210:213], v[218:221], v[70:73]
	ds_read_b128 v[210:213], v182 offset:48
	ds_read_b128 v[214:217], v183 offset:33840
	ds_read_b128 v[218:221], v183 offset:42288
	v_pk_mul_f32 v[40:41], v[104:105], v[40:41]
	v_pk_mul_f32 v[38:39], v[106:107], v[38:39]
	s_waitcnt lgkmcnt(4)
	v_mfma_f32_16x16x32_bf16 v[74:77], v[188:191], v[192:195], v[74:77]
	s_add_i32 s39, s39, -1
	v_lshl_add_u64 v[114:115], v[114:115], 0, s[34:35]
	v_lshl_add_u64 v[116:117], v[116:117], 0, s[86:87]
	s_waitcnt lgkmcnt(3)
	v_mfma_f32_16x16x32_bf16 v[70:73], v[188:191], v[206:209], v[70:73]
	ds_read_b128 v[188:191], v182 offset:64
	ds_read_b128 v[192:195], v183 offset:33856
	ds_read_b128 v[206:209], v183 offset:42304
	v_lshl_add_u64 v[118:119], v[118:119], 0, s[86:87]
	v_lshl_add_u64 v[120:121], v[120:121], 0, s[86:87]
	s_waitcnt lgkmcnt(4)
	v_mfma_f32_16x16x32_bf16 v[74:77], v[210:213], v[214:217], v[74:77]
	v_lshl_add_u64 v[122:123], v[122:123], 0, s[86:87]
	s_cmp_lg_u32 s39, 0
	s_waitcnt lgkmcnt(3)
	v_mfma_f32_16x16x32_bf16 v[70:73], v[210:213], v[218:221], v[70:73]
	ds_read_b128 v[210:213], v182 offset:80
	ds_read_b128 v[214:217], v183 offset:33872
	ds_read_b128 v[218:221], v183 offset:42320
	s_waitcnt lgkmcnt(4)
	v_mfma_f32_16x16x32_bf16 v[74:77], v[188:191], v[192:195], v[74:77]
	s_waitcnt lgkmcnt(3)
	v_mfma_f32_16x16x32_bf16 v[70:73], v[188:191], v[206:209], v[70:73]
	ds_read_b128 v[188:191], v182 offset:96
	ds_read_b128 v[192:195], v183 offset:33888
	ds_read_b128 v[206:209], v183 offset:42336
	s_waitcnt lgkmcnt(4)
	v_mfma_f32_16x16x32_bf16 v[74:77], v[210:213], v[214:217], v[74:77]
	s_waitcnt lgkmcnt(3)
	v_mfma_f32_16x16x32_bf16 v[70:73], v[210:213], v[218:221], v[70:73]
	ds_read_b128 v[210:213], v182 offset:112
	ds_read_b128 v[214:217], v183 offset:33904
	ds_read_b128 v[218:221], v183 offset:42352
	s_waitcnt lgkmcnt(4)
	v_mfma_f32_16x16x32_bf16 v[74:77], v[188:191], v[192:195], v[74:77]
	s_waitcnt lgkmcnt(3)
	v_mfma_f32_16x16x32_bf16 v[70:73], v[188:191], v[206:209], v[70:73]
	s_waitcnt lgkmcnt(1)
	v_mfma_f32_16x16x32_bf16 v[74:77], v[210:213], v[214:217], v[74:77]
	s_waitcnt lgkmcnt(0)
	v_mfma_f32_16x16x32_bf16 v[70:73], v[210:213], v[218:221], v[70:73]
	s_nop 5
	v_mul_f32_e32 v1, v103, v74
	v_cvt_pk_bf16_f32 v1, v1, s0
	v_add_u32_e32 v74, v131, v126
	ds_write_b16 v74, v1
	v_add_u32_e32 v206, v134, v127
	v_mul_f32_e32 v1, v198, v70
	v_cvt_pk_bf16_f32 v1, v1, s0
	ds_write_b16 v205, v1
	v_mul_f32_e32 v1, v199, v75
	v_cvt_pk_bf16_f32 v1, v1, s0
	v_add_u32_e32 v75, v134, v126
	ds_write_b16 v75, v1
	v_mul_f32_e32 v1, v200, v71
	v_cvt_pk_bf16_f32 v1, v1, s0
	ds_write_b16 v206, v1
	v_mul_f32_e32 v1, v201, v76
	v_cvt_pk_bf16_f32 v1, v1, s0
	v_add_u32_e32 v76, v137, v126
	ds_write_b16 v76, v1
	v_mul_f32_e32 v1, v202, v72
	v_cvt_pk_bf16_f32 v1, v1, s0
	v_add_u32_e32 v207, v137, v127
	ds_write_b16 v207, v1
	v_mul_f32_e32 v1, v203, v77
	v_cvt_pk_bf16_f32 v1, v1, s0
	v_add_u32_e32 v77, v140, v126
	ds_write_b16 v77, v1
	v_mul_f32_e32 v1, v204, v73
	v_cvt_pk_bf16_f32 v1, v1, s0
	v_add_u32_e32 v208, v140, v127
	ds_write_b16 v208, v1
	s_waitcnt lgkmcnt(0)
	s_barrier
	ds_read_b128 v[70:73], v182
	ds_read_b128 v[188:191], v184
	ds_read_b128 v[192:195], v184 offset:8448
	ds_read_b128 v[222:225], v182 offset:16
	ds_read_b128 v[218:221], v184 offset:16
	ds_read_b128 v[242:245], v184 offset:8464
	s_waitcnt lgkmcnt(4)
	v_mfma_f32_16x16x32_bf16 v[188:191], v[188:191], v[70:73], 0
	s_waitcnt lgkmcnt(3)
	v_mfma_f32_16x16x32_bf16 v[70:73], v[192:195], v[70:73], 0
	ds_read_b128 v[192:195], v182 offset:32
	ds_read_b128 v[210:213], v184 offset:32
	ds_read_b128 v[214:217], v184 offset:8480
	s_waitcnt lgkmcnt(4)
	v_mfma_f32_16x16x32_bf16 v[188:191], v[218:221], v[222:225], v[188:191]
	s_waitcnt lgkmcnt(3)
	v_mfma_f32_16x16x32_bf16 v[70:73], v[242:245], v[222:225], v[70:73]
	ds_read_b128 v[222:225], v182 offset:48
	ds_read_b128 v[218:221], v184 offset:48
	ds_read_b128 v[242:245], v184 offset:8496
	s_waitcnt lgkmcnt(4)
	v_mfma_f32_16x16x32_bf16 v[188:191], v[210:213], v[192:195], v[188:191]
	s_waitcnt lgkmcnt(3)
	v_mfma_f32_16x16x32_bf16 v[70:73], v[214:217], v[192:195], v[70:73]
	ds_read_b128 v[192:195], v182 offset:64
	ds_read_b128 v[210:213], v184 offset:64
	ds_read_b128 v[214:217], v184 offset:8512
	s_waitcnt lgkmcnt(4)
	v_mfma_f32_16x16x32_bf16 v[188:191], v[218:221], v[222:225], v[188:191]
	s_waitcnt lgkmcnt(3)
	v_mfma_f32_16x16x32_bf16 v[70:73], v[242:245], v[222:225], v[70:73]
	ds_read_b128 v[222:225], v182 offset:80
	ds_read_b128 v[218:221], v184 offset:80
	ds_read_b128 v[242:245], v184 offset:8528
	s_waitcnt lgkmcnt(4)
	v_mfma_f32_16x16x32_bf16 v[188:191], v[210:213], v[192:195], v[188:191]
	s_waitcnt lgkmcnt(3)
	v_mfma_f32_16x16x32_bf16 v[70:73], v[214:217], v[192:195], v[70:73]
	ds_read_b128 v[192:195], v182 offset:96
	ds_read_b128 v[210:213], v184 offset:96
	ds_read_b128 v[214:217], v184 offset:8544
	s_waitcnt lgkmcnt(4)
	v_mfma_f32_16x16x32_bf16 v[188:191], v[218:221], v[222:225], v[188:191]
	s_waitcnt lgkmcnt(3)
	v_mfma_f32_16x16x32_bf16 v[70:73], v[242:245], v[222:225], v[70:73]
	ds_read_b128 v[222:225], v182 offset:112
	ds_read_b128 v[218:221], v184 offset:112
	ds_read_b128 v[242:245], v184 offset:8560
	s_waitcnt lgkmcnt(4)
	v_mfma_f32_16x16x32_bf16 v[188:191], v[210:213], v[192:195], v[188:191]
	s_waitcnt lgkmcnt(3)
	v_mfma_f32_16x16x32_bf16 v[70:73], v[214:217], v[192:195], v[70:73]
	s_waitcnt lgkmcnt(1)
	v_mfma_f32_16x16x32_bf16 v[188:191], v[218:221], v[222:225], v[188:191]
	s_waitcnt lgkmcnt(0)
	v_mfma_f32_16x16x32_bf16 v[70:73], v[242:245], v[222:225], v[70:73]
	ds_read_b128 v[192:195], v185
	s_nop 4
	v_pk_mul_f32 v[190:191], v[110:111], v[190:191]
	v_pk_mul_f32 v[188:189], v[108:109], v[188:189]
	ds_read_b64_tr_b16 v[214:215], v141
	ds_read_b64_tr_b16 v[216:217], v142
	ds_read_b64_tr_b16 v[210:211], v143
	ds_read_b64_tr_b16 v[212:213], v144
	s_waitcnt lgkmcnt(0)
	s_waitcnt lgkmcnt(0)
	s_nop 0
	v_mfma_f32_16x16x32_bf16 v[188:191], v[214:217], v[192:195], v[188:191]
	v_mul_f32_e64 v72, v110, v72
	v_mul_f32_e64 v73, v111, v73
	v_pk_mul_f32 v[70:71], v[108:109], v[70:71]
	s_nop 1
	v_mfma_f32_16x16x32_bf16 v[70:73], v[210:213], v[192:195], v[70:73]
	ds_read_b128 v[192:195], v185 offset:64
	ds_read_b64_tr_b16 v[214:215], v145
	ds_read_b64_tr_b16 v[216:217], v146
	ds_read_b64_tr_b16 v[210:211], v147
	ds_read_b64_tr_b16 v[212:213], v148
	s_waitcnt lgkmcnt(0)
	s_waitcnt lgkmcnt(0)
	v_mfma_f32_16x16x32_bf16 v[188:191], v[214:217], v[192:195], v[188:191]
	v_mfma_f32_16x16x32_bf16 v[192:195], v[210:213], v[192:195], v[70:73]
	s_nop 6
	v_cvt_pk_bf16_f32 v70, v188, v189
	v_lshl_add_u64 v[188:189], s[78:79], 0, v[112:113]
	v_add_co_u32_e64 v188, s[36:37], s36, v188
	v_cvt_pk_bf16_f32 v71, v190, v191
	s_nop 0
	v_addc_co_u32_e64 v189, s[36:37], 0, v189, s[36:37]
	v_cvt_pk_bf16_f32 v72, v192, v193
	v_cvt_pk_bf16_f32 v73, v194, v195
	global_store_dwordx2 v[188:189], v[70:71], off
	global_store_dwordx2 v[188:189], v[72:73], off offset:32
	v_pk_mul_f32 v[72:73], v[104:105], v[52:53]
	v_pk_mul_f32 v[70:71], v[106:107], v[50:51]
	v_pk_mul_f32 v[52:53], v[104:105], v[56:57]
	v_pk_mul_f32 v[50:51], v[106:107], v[54:55]
	ds_read_b64_tr_b16 v[188:189], v149
	ds_read_b64_tr_b16 v[190:191], v151
	ds_read_b64_tr_b16 v[54:55], v152
	ds_read_b64_tr_b16 v[56:57], v153
	ds_read_b64_tr_b16 v[210:211], v150
	ds_read_b64_tr_b16 v[212:213], v154
	ds_read_b64_tr_b16 v[192:193], v155
	ds_read_b64_tr_b16 v[194:195], v156
	ds_read_b64_tr_b16 v[218:219], v157
	ds_read_b64_tr_b16 v[220:221], v158
	ds_read_b64_tr_b16 v[214:215], v159
	ds_read_b64_tr_b16 v[216:217], v160
	s_waitcnt lgkmcnt(0)
	v_lshl_add_u64 v[112:113], v[112:113], 0, s[34:35]
	v_mfma_f32_16x16x32_bf16 v[66:69], v[188:191], v[210:213], v[66:69]
	v_mfma_f32_16x16x32_bf16 v[62:65], v[188:191], v[192:195], v[62:65]
	v_mfma_f32_16x16x32_bf16 v[58:61], v[188:191], v[218:221], v[58:61]
	v_mfma_f32_16x16x32_bf16 v[70:73], v[188:191], v[214:217], v[70:73]
	v_mfma_f32_16x16x32_bf16 v[188:191], v[54:57], v[210:213], v[50:53]
	v_mfma_f32_16x16x32_bf16 v[46:49], v[54:57], v[192:195], v[46:49]
	ds_read_b64_tr_b16 v[50:51], v161
	ds_read_b64_tr_b16 v[52:53], v163
	ds_read_b64_tr_b16 v[192:193], v164
	ds_read_b64_tr_b16 v[194:195], v165
	s_waitcnt lgkmcnt(0)
	v_mfma_f32_16x16x32_bf16 v[42:45], v[54:57], v[218:221], v[42:45]
	v_mfma_f32_16x16x32_bf16 v[38:41], v[54:57], v[214:217], v[38:41]
	ds_read_b64_tr_b16 v[54:55], v162
	ds_read_b64_tr_b16 v[56:57], v166
	ds_read_b64_tr_b16 v[210:211], v167
	ds_read_b64_tr_b16 v[212:213], v168
	s_waitcnt lgkmcnt(0)
	ds_read_b64_tr_b16 v[218:219], v169
	ds_read_b64_tr_b16 v[220:221], v170
	ds_read_b64_tr_b16 v[214:215], v171
	ds_read_b64_tr_b16 v[216:217], v172
	s_waitcnt lgkmcnt(0)
	s_nop 0
	v_mfma_f32_16x16x32_bf16 v[66:69], v[50:53], v[54:57], v[66:69]
	s_barrier
	v_mfma_f32_16x16x32_bf16 v[62:65], v[50:53], v[210:213], v[62:65]
	v_mfma_f32_16x16x32_bf16 v[58:61], v[50:53], v[218:221], v[58:61]
	v_mfma_f32_16x16x32_bf16 v[50:53], v[50:53], v[214:217], v[70:73]
	v_mfma_f32_16x16x32_bf16 v[54:57], v[192:195], v[54:57], v[188:191]
	s_nop 2
	v_cvt_pk_bf16_f32 v70, v66, v67
	v_cvt_pk_bf16_f32 v71, v68, v69
	ds_write_b64 v196, v[70:71]
	v_mfma_f32_16x16x32_bf16 v[46:49], v[192:195], v[210:213], v[46:49]
	v_cvt_pk_bf16_f32 v70, v62, v63
	v_cvt_pk_bf16_f32 v71, v64, v65
	ds_write_b64 v196, v[70:71] offset:8448
	v_mfma_f32_16x16x32_bf16 v[42:45], v[192:195], v[218:221], v[42:45]
	v_cvt_pk_bf16_f32 v70, v58, v59
	v_cvt_pk_bf16_f32 v71, v60, v61
	ds_write_b64 v196, v[70:71] offset:16896
	v_mfma_f32_16x16x32_bf16 v[38:41], v[192:195], v[214:217], v[38:41]
	v_cvt_pk_bf16_f32 v70, v50, v51
	v_cvt_pk_bf16_f32 v71, v52, v53
	ds_write_b64 v196, v[70:71] offset:25344
	v_cvt_pk_bf16_f32 v70, v54, v55
	v_cvt_pk_bf16_f32 v71, v56, v57
	ds_write_b64 v197, v[70:71]
	v_cvt_pk_bf16_f32 v70, v46, v47
	v_cvt_pk_bf16_f32 v71, v48, v49
	ds_write_b64 v197, v[70:71] offset:8448
	v_cvt_pk_bf16_f32 v70, v42, v43
	v_cvt_pk_bf16_f32 v71, v44, v45
	ds_write_b64 v197, v[70:71] offset:16896
	v_cvt_pk_bf16_f32 v70, v38, v39
	v_cvt_pk_bf16_f32 v71, v40, v41
	ds_write_b64 v197, v[70:71] offset:25344
	s_cbranch_scc1 .LBB0_438
	s_waitcnt vmcnt(10)
	ds_write_b128 v176, v[2:5]
	s_waitcnt vmcnt(7)
	ds_write_b128 v176, v[6:9] offset:33792
	s_waitcnt vmcnt(6)
	ds_write_b128 v177, v[10:13]
	s_waitcnt vmcnt(5)
	ds_write_b128 v177, v[14:17] offset:33792
	s_waitcnt vmcnt(4)
	ds_write_b128 v178, v[18:21]
	s_waitcnt vmcnt(3)
	ds_write_b128 v178, v[22:25] offset:33792
	ds_write_b128 v179, v[30:33]
	ds_write_b128 v179, v[34:37] offset:33792
	s_waitcnt vmcnt(2)
	ds_write_b128 v180, v[26:29]
	v_lshlrev_b32_e32 v2, 16, v26
	v_and_b32_e32 v3, 0xffff0000, v26
	v_lshlrev_b32_e32 v4, 16, v27
	v_and_b32_e32 v5, 0xffff0000, v27
	v_pk_mul_f32 v[2:3], v[124:125], v[2:3]
	v_pk_mul_f32 v[4:5], v[124:125], v[4:5]
	v_cvt_pk_bf16_f32 v2, v2, v3
	v_cvt_pk_bf16_f32 v3, v4, v5
	v_lshlrev_b32_e32 v4, 16, v28
	v_and_b32_e32 v5, 0xffff0000, v28
	v_lshlrev_b32_e32 v6, 16, v29
	v_and_b32_e32 v7, 0xffff0000, v29
	v_pk_mul_f32 v[4:5], v[124:125], v[4:5]
	v_pk_mul_f32 v[6:7], v[124:125], v[6:7]
	v_cvt_pk_bf16_f32 v4, v4, v5
	v_cvt_pk_bf16_f32 v5, v6, v7
	ds_write_b128 v181, v[2:5]
	s_waitcnt lgkmcnt(0)
	s_barrier
	ds_read_b128 v[2:5], v182
	ds_read_b128 v[6:9], v183 offset:33792
	ds_read_b128 v[10:13], v182 offset:16
	ds_read_b128 v[14:17], v183 offset:33808
	s_waitcnt lgkmcnt(2)
	v_mfma_f32_16x16x32_bf16 v[6:9], v[2:5], v[6:9], 0
	ds_read_b128 v[18:21], v183 offset:42240
	ds_read_b128 v[22:25], v183 offset:42256
	s_lshl_b32 s15, s15, 1
	s_add_u32 s15, s7, s15
	s_waitcnt lgkmcnt(2)
	v_mfma_f32_16x16x32_bf16 v[6:9], v[10:13], v[14:17], v[6:9]
	ds_read_b128 v[14:17], v182 offset:32
	s_addc_u32 s39, s10, 0
	s_lshl_b64 s[36:37], s[40:41], 1
	s_waitcnt lgkmcnt(2)
	v_mfma_f32_16x16x32_bf16 v[2:5], v[2:5], v[18:21], 0
	s_add_u32 s36, s15, s36
	s_addc_u32 s37, s39, s37
	v_pk_mul_f32 v[30:31], v[104:105], v[60:61]
	s_waitcnt lgkmcnt(1)
	v_mfma_f32_16x16x32_bf16 v[2:5], v[10:13], v[22:25], v[2:5]
	ds_read_b128 v[10:13], v183 offset:33824
	ds_read_b128 v[18:21], v182 offset:48
	ds_read_b128 v[22:25], v183 offset:33840
	v_pk_mul_f32 v[52:53], v[104:105], v[52:53]
	v_pk_mul_f32 v[50:51], v[106:107], v[50:51]
	s_waitcnt lgkmcnt(2)
	v_mfma_f32_16x16x32_bf16 v[6:9], v[14:17], v[10:13], v[6:9]
	ds_read_b128 v[10:13], v183 offset:42272
	ds_read_b128 v[26:29], v183 offset:42288
	v_pk_mul_f32 v[48:49], v[104:105], v[48:49]
	v_pk_mul_f32 v[46:47], v[106:107], v[46:47]
	s_waitcnt lgkmcnt(1)
	v_mfma_f32_16x16x32_bf16 v[2:5], v[14:17], v[10:13], v[2:5]
	ds_read_b128 v[10:13], v182 offset:64
	v_pk_mul_f32 v[44:45], v[104:105], v[44:45]
	v_pk_mul_f32 v[42:43], v[106:107], v[42:43]
	v_mfma_f32_16x16x32_bf16 v[6:9], v[18:21], v[22:25], v[6:9]
	v_mul_f32_e64 v40, v104, v40
	v_mul_f32_e64 v41, v105, v41
	v_pk_mul_f32 v[38:39], v[106:107], v[38:39]
	s_add_i32 s14, s14, s85
	s_waitcnt lgkmcnt(1)
	v_mfma_f32_16x16x32_bf16 v[2:5], v[18:21], v[26:29], v[2:5]
	ds_read_b128 v[14:17], v183 offset:33856
	ds_read_b128 v[18:21], v182 offset:80
	ds_read_b128 v[22:25], v183 offset:33872
	s_add_i32 s13, s13, s50
	s_add_i32 s12, s12, s85
	s_waitcnt lgkmcnt(2)
	v_mfma_f32_16x16x32_bf16 v[6:9], v[10:13], v[14:17], v[6:9]
	ds_read_b128 v[14:17], v183 offset:42304
	ds_read_b128 v[26:29], v183 offset:42320
	s_add_i32 s11, s11, s51
	s_waitcnt lgkmcnt(1)
	v_mfma_f32_16x16x32_bf16 v[2:5], v[10:13], v[14:17], v[2:5]
	ds_read_b128 v[10:13], v182 offset:96
	v_mfma_f32_16x16x32_bf16 v[6:9], v[18:21], v[22:25], v[6:9]
	s_waitcnt lgkmcnt(1)
	v_mfma_f32_16x16x32_bf16 v[2:5], v[18:21], v[26:29], v[2:5]
	ds_read_b128 v[14:17], v183 offset:33888
	ds_read_b128 v[18:21], v182 offset:112
	ds_read_b128 v[22:25], v183 offset:33904
	s_waitcnt lgkmcnt(2)
	v_mfma_f32_16x16x32_bf16 v[6:9], v[10:13], v[14:17], v[6:9]
	ds_read_b128 v[14:17], v183 offset:42336
	ds_read_b128 v[26:29], v183 offset:42352
	s_waitcnt lgkmcnt(1)
	v_mfma_f32_16x16x32_bf16 v[2:5], v[10:13], v[14:17], v[2:5]
	v_mfma_f32_16x16x32_bf16 v[6:9], v[18:21], v[22:25], v[6:9]
	s_waitcnt lgkmcnt(0)
	v_mfma_f32_16x16x32_bf16 v[2:5], v[18:21], v[26:29], v[2:5]
	s_nop 5
	v_mul_f32_e32 v1, v103, v6
	v_cvt_pk_bf16_f32 v1, v1, s0
	ds_write_b16 v74, v1
	v_mul_f32_e32 v1, v198, v2
	v_cvt_pk_bf16_f32 v1, v1, s0
	ds_write_b16 v205, v1
	v_mul_f32_e32 v1, v199, v7
	v_cvt_pk_bf16_f32 v1, v1, s0
	ds_write_b16 v75, v1
	v_mul_f32_e32 v1, v200, v3
	v_cvt_pk_bf16_f32 v1, v1, s0
	ds_write_b16 v206, v1
	v_mul_f32_e32 v1, v201, v8
	v_cvt_pk_bf16_f32 v1, v1, s0
	ds_write_b16 v76, v1
	v_mul_f32_e32 v1, v202, v4
	v_cvt_pk_bf16_f32 v1, v1, s0
	ds_write_b16 v207, v1
	v_mul_f32_e32 v1, v203, v9
	v_cvt_pk_bf16_f32 v1, v1, s0
	ds_write_b16 v77, v1
	v_mul_f32_e32 v1, v204, v5
	v_cvt_pk_bf16_f32 v1, v1, s0
	ds_write_b16 v208, v1
	s_waitcnt lgkmcnt(0)
	s_barrier
	ds_read_b128 v[2:5], v184
	ds_read_b128 v[6:9], v182
	ds_read_b128 v[10:13], v182 offset:16
	ds_read_b128 v[14:17], v184 offset:16
	s_waitcnt lgkmcnt(2)
	v_mfma_f32_16x16x32_bf16 v[2:5], v[2:5], v[6:9], 0
	ds_read_b128 v[18:21], v184 offset:8448
	ds_read_b128 v[22:25], v184 offset:8464
	s_waitcnt lgkmcnt(2)
	v_mfma_f32_16x16x32_bf16 v[2:5], v[14:17], v[10:13], v[2:5]
	ds_read_b128 v[14:17], v184 offset:32
	s_waitcnt lgkmcnt(2)
	v_mfma_f32_16x16x32_bf16 v[6:9], v[18:21], v[6:9], 0
	s_waitcnt lgkmcnt(1)
	v_mfma_f32_16x16x32_bf16 v[6:9], v[22:25], v[10:13], v[6:9]
	ds_read_b128 v[10:13], v182 offset:32
	ds_read_b128 v[18:21], v182 offset:48
	ds_read_b128 v[22:25], v184 offset:48
	s_waitcnt lgkmcnt(2)
	v_mfma_f32_16x16x32_bf16 v[2:5], v[14:17], v[10:13], v[2:5]
	ds_read_b128 v[14:17], v184 offset:8480
	ds_read_b128 v[26:29], v184 offset:8496
	s_waitcnt lgkmcnt(1)
	v_mfma_f32_16x16x32_bf16 v[6:9], v[14:17], v[10:13], v[6:9]
	ds_read_b128 v[10:13], v184 offset:64
	v_mfma_f32_16x16x32_bf16 v[2:5], v[22:25], v[18:21], v[2:5]
	s_waitcnt lgkmcnt(1)
	v_mfma_f32_16x16x32_bf16 v[6:9], v[26:29], v[18:21], v[6:9]
	ds_read_b128 v[14:17], v182 offset:64
	ds_read_b128 v[18:21], v182 offset:80
	ds_read_b128 v[22:25], v184 offset:80
	s_waitcnt lgkmcnt(2)
	v_mfma_f32_16x16x32_bf16 v[2:5], v[10:13], v[14:17], v[2:5]
	ds_read_b128 v[10:13], v184 offset:8512
	ds_read_b128 v[26:29], v184 offset:8528
	s_waitcnt lgkmcnt(1)
	v_mfma_f32_16x16x32_bf16 v[6:9], v[10:13], v[14:17], v[6:9]
	ds_read_b128 v[10:13], v184 offset:96
	v_mfma_f32_16x16x32_bf16 v[2:5], v[22:25], v[18:21], v[2:5]
	s_waitcnt lgkmcnt(1)
	v_mfma_f32_16x16x32_bf16 v[6:9], v[26:29], v[18:21], v[6:9]
	ds_read_b128 v[14:17], v182 offset:96
	ds_read_b128 v[18:21], v182 offset:112
	ds_read_b128 v[22:25], v184 offset:112
	s_waitcnt lgkmcnt(2)
	v_mfma_f32_16x16x32_bf16 v[2:5], v[10:13], v[14:17], v[2:5]
	ds_read_b128 v[10:13], v184 offset:8544
	ds_read_b128 v[26:29], v184 offset:8560
	s_waitcnt lgkmcnt(1)
	v_mfma_f32_16x16x32_bf16 v[6:9], v[10:13], v[14:17], v[6:9]
	ds_read_b128 v[10:13], v185
	v_mfma_f32_16x16x32_bf16 v[2:5], v[22:25], v[18:21], v[2:5]
	s_waitcnt lgkmcnt(1)
	v_mfma_f32_16x16x32_bf16 v[6:9], v[26:29], v[18:21], v[6:9]
	ds_read_b64_tr_b16 v[18:19], v141
	ds_read_b64_tr_b16 v[20:21], v142
	ds_read_b64_tr_b16 v[14:15], v143
	ds_read_b64_tr_b16 v[16:17], v144
	s_waitcnt lgkmcnt(0)
	s_nop 5
	v_mul_f32_e64 v4, v110, v4
	v_mul_f32_e64 v5, v111, v5
	v_pk_mul_f32 v[2:3], v[108:109], v[2:3]
	v_pk_mul_f32 v[28:29], v[106:107], v[58:59]
	s_waitcnt lgkmcnt(0)
	v_mfma_f32_16x16x32_bf16 v[2:5], v[18:21], v[10:13], v[2:5]
	v_mul_f32_e64 v8, v110, v8
	v_mul_f32_e64 v9, v111, v9
	v_pk_mul_f32 v[6:7], v[108:109], v[6:7]
	s_nop 1
	v_mfma_f32_16x16x32_bf16 v[6:9], v[14:17], v[10:13], v[6:9]
	ds_read_b128 v[10:13], v185 offset:64
	ds_read_b64_tr_b16 v[18:19], v145
	ds_read_b64_tr_b16 v[20:21], v146
	ds_read_b64_tr_b16 v[14:15], v147
	ds_read_b64_tr_b16 v[16:17], v148
	s_waitcnt lgkmcnt(0)
	s_waitcnt lgkmcnt(0)
	v_mfma_f32_16x16x32_bf16 v[2:5], v[18:21], v[10:13], v[2:5]
	v_lshl_add_u64 v[18:19], s[36:37], 0, v[186:187]
	s_or_b32 s36, s38, 0xfc0
	s_mov_b32 s37, s57
	v_mfma_f32_16x16x32_bf16 v[6:9], v[14:17], v[10:13], v[6:9]
	v_lshl_add_u64 v[10:11], v[80:81], 0, s[36:37]
	v_lshl_add_u64 v[18:19], v[18:19], 0, s[56:57]
	s_nop 1
	v_cvt_pk_bf16_f32 v2, v2, v3
	v_cvt_pk_bf16_f32 v3, v4, v5
	s_cmpk_lt_i32 s14, 0x100
	s_nop 0
	v_cvt_pk_bf16_f32 v4, v6, v7
	v_lshlrev_b64 v[6:7], 13, v[10:11]
	v_lshl_add_u64 v[6:7], v[18:19], 0, v[6:7]
	v_cvt_pk_bf16_f32 v5, v8, v9
	global_store_dwordx2 v[6:7], v[2:3], off
	global_store_dwordx2 v[6:7], v[4:5], off offset:32
	v_pk_mul_f32 v[4:5], v[104:105], v[68:69]
	v_pk_mul_f32 v[2:3], v[106:107], v[66:67]
	ds_read_b64_tr_b16 v[12:13], v149
	ds_read_b64_tr_b16 v[14:15], v151
	ds_read_b64_tr_b16 v[8:9], v152
	ds_read_b64_tr_b16 v[10:11], v153
	s_waitcnt lgkmcnt(0)
	v_pk_mul_f32 v[6:7], v[104:105], v[64:65]
	ds_read_b64_tr_b16 v[20:21], v150
	ds_read_b64_tr_b16 v[22:23], v154
	ds_read_b64_tr_b16 v[16:17], v155
	ds_read_b64_tr_b16 v[18:19], v156
	s_waitcnt lgkmcnt(0)
	ds_read_b64_tr_b16 v[58:59], v157
	ds_read_b64_tr_b16 v[60:61], v158
	ds_read_b64_tr_b16 v[32:33], v159
	ds_read_b64_tr_b16 v[34:35], v160
	s_waitcnt lgkmcnt(0)
	s_nop 0
	v_mfma_f32_16x16x32_bf16 v[24:27], v[12:15], v[20:23], v[2:5]
	s_nop 2
	v_mul_f32_e64 v4, v106, v62
	v_mul_f32_e64 v5, v107, v63
	v_mfma_f32_16x16x32_bf16 v[28:31], v[12:15], v[58:61], v[28:31]
	s_nop 0
	v_mfma_f32_16x16x32_bf16 v[2:5], v[12:15], v[16:19], v[4:7]
	v_mfma_f32_16x16x32_bf16 v[12:15], v[12:15], v[32:35], v[50:53]
	s_nop 2
	v_mul_f32_e64 v52, v104, v56
	v_mul_f32_e64 v53, v105, v57
	v_pk_mul_f32 v[50:51], v[106:107], v[54:55]
	v_mfma_f32_16x16x32_bf16 v[16:19], v[8:11], v[16:19], v[46:49]
	s_nop 0
	v_mfma_f32_16x16x32_bf16 v[20:23], v[8:11], v[20:23], v[50:53]
	v_mfma_f32_16x16x32_bf16 v[42:45], v[8:11], v[58:61], v[42:45]
	v_mfma_f32_16x16x32_bf16 v[6:9], v[8:11], v[32:35], v[38:41]
	ds_read_b64_tr_b16 v[36:37], v161
	ds_read_b64_tr_b16 v[38:39], v163
	ds_read_b64_tr_b16 v[32:33], v164
	ds_read_b64_tr_b16 v[34:35], v165
	s_waitcnt lgkmcnt(0)
	ds_read_b64_tr_b16 v[50:51], v162
	ds_read_b64_tr_b16 v[52:53], v166
	ds_read_b64_tr_b16 v[46:47], v167
	ds_read_b64_tr_b16 v[48:49], v168
	s_waitcnt lgkmcnt(0)
	ds_read_b64_tr_b16 v[58:59], v169
	ds_read_b64_tr_b16 v[60:61], v170
	ds_read_b64_tr_b16 v[54:55], v171
	ds_read_b64_tr_b16 v[56:57], v172
	s_waitcnt lgkmcnt(0)
	s_nop 0
	v_mfma_f32_16x16x32_bf16 v[2:5], v[36:39], v[46:49], v[2:5]
	s_barrier
	v_mfma_f32_16x16x32_bf16 v[28:31], v[36:39], v[58:61], v[28:31]
	v_mfma_f32_16x16x32_bf16 v[10:13], v[36:39], v[54:57], v[12:15]
	s_nop 4
	v_cvt_pk_bf16_f32 v2, v2, v3
	v_cvt_pk_bf16_f32 v3, v4, v5
	ds_write_b64 v196, v[2:3] offset:8448
	v_mfma_f32_16x16x32_bf16 v[20:23], v[32:35], v[50:53], v[20:23]
	v_cvt_pk_bf16_f32 v2, v28, v29
	v_cvt_pk_bf16_f32 v3, v30, v31
	ds_write_b64 v196, v[2:3] offset:16896
	v_mfma_f32_16x16x32_bf16 v[14:17], v[32:35], v[46:49], v[16:19]
	v_cvt_pk_bf16_f32 v2, v10, v11
	v_cvt_pk_bf16_f32 v3, v12, v13
	ds_write_b64 v196, v[2:3] offset:25344
	v_mfma_f32_16x16x32_bf16 v[24:27], v[36:39], v[50:53], v[24:27]
	v_cvt_pk_bf16_f32 v2, v20, v21
	v_cvt_pk_bf16_f32 v3, v22, v23
	ds_write_b64 v197, v[2:3]
	v_mfma_f32_16x16x32_bf16 v[36:39], v[32:35], v[58:61], v[42:45]
	v_cvt_pk_bf16_f32 v2, v14, v15
	v_cvt_pk_bf16_f32 v3, v16, v17
	ds_write_b64 v197, v[2:3] offset:8448
	v_mfma_f32_16x16x32_bf16 v[6:9], v[32:35], v[54:57], v[6:9]
	v_cvt_pk_bf16_f32 v18, v24, v25
	s_nop 2
	v_cvt_pk_bf16_f32 v2, v36, v37
	v_cvt_pk_bf16_f32 v3, v38, v39
	v_cvt_pk_bf16_f32 v19, v26, v27
	ds_write_b64 v197, v[2:3] offset:16896
	v_cvt_pk_bf16_f32 v2, v6, v7
	v_cvt_pk_bf16_f32 v3, v8, v9
	ds_write_b64 v196, v[18:19]
	ds_write_b64 v197, v[2:3] offset:25344
	s_waitcnt lgkmcnt(0)
	s_barrier
	s_cbranch_scc1 .LBB0_434
